# idlew2: this layer's FFN2 weight conversion (prologue items 4224..8447) moved into the FFN1-up last-round idle slots of workgroups 144..255, both layers
# speedup vs baseline: 1.0143x; 1.0096x over previous
; __device__ __forceinline__ void prologue(Frame& F, const Args& A, int l) {
;     ...
;     for (int it = gw; it < NITEMS; it += NGW) {
;         int r = it, si, sci = -1, K = DM, N = FFH, rs = 128, off = 0, nblk = 32; size_t so = oFF, dsto;
;         if (r < 6 * 1408) { const int w = r / 1408; r -= w * 1408; const int second = w >= 3, t = w % 3;
.LBB0_11:
	s_cmpk_lt_i32 s13, 0x1080
	s_cbranch_scc1 .Lpro_keepw2
	s_cmpk_gt_i32 s13, 0x20ff
	s_cbranch_scc1 .Lpro_keepw2
	s_add_i32 s13, s13, s12
	s_cmpk_gt_i32 s13, 0x307f
	s_cbranch_scc1 .LBB0_49
	s_branch .LBB0_11

; __device__ __forceinline__ void transpose_item(const float* W, int K, int N, bf16* WT, int rs, int off, const float* sc, LAS float* scr, int item, int nblk, int lane, int swp) {
;     const int kb = item / nblk, nb = item % nblk, k0 = 64 * kb, n0 = 32 * nb;
;     const int n = n0 + (lane & 31);
;     float tv[32];
; #pragma unroll
;     for (int i = 0; i < 32; ++i) tv[i] = 0.f;
;     if (n < N) { const float* p = W + (size_t)(k0 + (lane >> 5)) * N + n; int stepv = 2 * N; asm volatile("" : "+v"(stepv));
; #pragma unroll
;         for (int i = 0; i < 32; ++i) { tv[i] = *p; p += stepv; } }
; #pragma unroll
;     for (int i = 0; i < 32; ++i) scr[(2 * i + (lane >> 5)) * 33 + (lane & 31)] = tv[i];
;     LDS_WAIT(); asm volatile("" ::: "memory");
;     const int c = lane & 7;
;     f32x4 s0 = {1.f, 1.f, 1.f, 1.f}, s1 = s0; if (sc) { s0 = *(const f32x4*)(sc + k0 + 8 * c); s1 = *(const f32x4*)(sc + k0 + 8 * c + 4); }
; #pragma unroll
;     for (int j = 0; j < 4; ++j) { const int nn = (lane >> 3) + 8 * j; const LAS float* s = scr + (8 * c) * 33 + nn;
;         v4u o; o.x = cvt_pk_bf16(s[0 * 33] * s0[0], s[1 * 33] * s0[1]); o.y = cvt_pk_bf16(s[2 * 33] * s0[2], s[3 * 33] * s0[3]); o.z = cvt_pk_bf16(s[4 * 33] * s1[0], s[5 * 33] * s1[1]); o.w = cvt_pk_bf16(s[6 * 33] * s1[2], s[7 * 33] * s1[3]);
;         const int ng = n0 + nn, t256 = ng >> 8, ts256 = (t256 == 2) ? 7 : (t256 == 7) ? 2 : t256, dr = swp ? ts256 * 256 + (ng & 255) : (ng / 128) * rs + off + (ng % 128);
;         *(v4u*)(WT + (size_t)dr * K + k0 + 8 * c) = o; }
; __device__ __forceinline__ void prologue(Frame& F, const Args& A, int l) {
;     ...
;     for (int it = gw; it < NITEMS; it += NGW) {
;         int r = it, si, sci = -1, K = DM, N = FFH, rs = 128, off = 0, nblk = 32; size_t so = oFF, dsto;
;         if (r < 6 * 1408) { const int w = r / 1408; r -= w * 1408; const int second = w >= 3, t = w % 3;
;             if (t < 2) { si = (second ? 19 : 3) + t; sci = second ? 18 : 2; rs = 256; off = 128 * t; nblk = 88; dsto = second ? WS_W2A : WS_W1A; }
;             else { si = second ? 21 : 5; K = FFH; N = DM; dsto = second ? WS_W2B : WS_W1B; } }
;         else { r -= 6 * 1408;
;             if (r < I_IN) { si = 7; sci = 6; N = NIN; nblk = 120; so = (size_t)l * DM * NIN; dsto = WS_WIN; }
;             else { r -= I_IN; const int w = r / I_SQ; r -= w * I_SQ; N = DM; so = oDD;
.LBB0_187:
	s_cmpk_lt_u32 s83, 0x90
	s_cbranch_scc1 .Lpj_exit
	v_readlane_b32 s90, v255, 24
	v_readlane_b32 s91, v255, 25
	s_nop 1
	v_readlane_b32 s4, v255, 20
	v_readlane_b32 s6, v255, 22
	v_readlane_b32 s7, v255, 23
	s_mov_b32 s1, s83
	s_mov_b32 s0, s56
	s_mov_b32 s2, s69
	v_readlane_b32 s5, v255, 21
	s_mov_b64 s[10:11], s[6:7]
	v_mov_b32_e32 v9, v203
	s_and_b32 s4, s0, 7
	s_cmp_lg_u32 s4, 0
	v_readfirstlane_b32 s4, v9
	s_cbranch_scc1 .Lpj_b8
	s_ashr_i32 s6, s1, 31
	s_lshr_b32 s6, s6, 29
	s_add_i32 s6, s1, s6
	s_ashr_i32 s7, s6, 3
	s_and_b32 s6, s6, -8
	s_ashr_i32 s5, s0, 3
	s_sub_i32 s1, s1, s6
	s_mul_i32 s1, s5, s1
	s_add_i32 s1, s1, s7
.Lpj_b8:
	s_ashr_i32 s35, s4, 6
	s_lshl_b32 s36, s1, 3
	v_readlane_b32 s4, v255, 18
	s_add_i32 s34, s83, 0xffffff70
	s_lshl_b32 s34, s34, 3
	s_add_i32 s34, s34, s35
	s_movk_i32 s12, 0x380
	s_lshl_b32 s4, s4, 10
	v_and_b32_e32 v20, 63, v9
	s_cmpk_gt_i32 s34, 0x20ff
	v_readlane_b32 s5, v255, 19
	s_cbranch_scc1 .Lpj_exit
	s_lshl_b32 s8, s35, 14
	s_mul_i32 s68, s4, 0xb00
	s_add_i32 s2, s2, s8
	v_and_b32_e32 v21, 31, v9
	v_lshrrev_b32_e32 v22, 5, v20
	v_and_b32_e32 v2, 7, v9
	v_lshrrev_b32_e32 v23, 3, v20
	s_mov_b32 s5, s69
	s_mov_b64 s[6:7], s[68:69]
	s_mul_i32 s68, s4, 0xe08
	v_lshl_add_u32 v0, v21, 2, s2
	v_mul_u32_u24_e32 v1, 0x84, v22
	v_lshlrev_b32_e32 v8, 3, v2
	v_mul_u32_u24_e32 v2, 0x420, v2
	v_lshlrev_b32_e32 v3, 2, v23
	s_lshl_b64 s[14:15], s[4:5], 10
	s_mov_b64 s[16:17], s[68:69]
	v_add3_u32 v24, s2, v2, v3
	v_or_b32_e32 v25, 8, v23
	v_or_b32_e32 v26, 16, v23
	v_or_b32_e32 v27, 24, v23
	v_add_u32_e32 v28, v0, v1
	v_lshlrev_b32_e32 v192, 1, v8
	s_lshr_b32 s13, s12, 1
	s_add_i32 s13, s34, s13
	s_cmp_ge_i32 s13, s12
	s_cbranch_scc0 .Lpj_Lpro_rot_ok
	s_sub_i32 s13, s13, s12
.Lpj_Lpro_rot_ok:
	s_addk_i32 s13, 0x1080
	s_branch .Lpj_b11
.Lpj_b10:
	s_waitcnt lgkmcnt(0)
	v_pk_mul_f32 v[4:5], v[4:5], v[18:19]
	v_pk_mul_f32 v[6:7], v[6:7], v[16:17]
	v_pk_mul_f32 v[0:1], v[0:1], v[14:15]
	v_cvt_pk_bf16_f32 v4, v4, v5
	v_cvt_pk_bf16_f32 v5, v6, v7
	v_cvt_pk_bf16_f32 v6, v0, v1
	v_pk_mul_f32 v[0:1], v[2:3], v[12:13]
	s_add_i32 s13, s13, s12
	v_cvt_pk_bf16_f32 v7, v0, v1
	v_mad_i64_i32 v[0:1], s[18:19], s18, v29, 0
	v_lshl_add_u64 v[0:1], v[0:1], 1, v[10:11]
	flat_store_dwordx4 v[0:1], v[4:7]
	s_waitcnt lgkmcnt(0)
	s_cmpk_gt_i32 s13, 0x20ff
	s_cbranch_scc1 .Lpj_exit

; __device__ __forceinline__ unsigned xb_add_u(unsigned* p, unsigned v, int lane) { unsigned r = 0u; if (lane == 0) r = __hip_atomic_fetch_add(p, v, RLX_AGENT); return (unsigned)__builtin_amdgcn_readfirstlane((int)r); }
; __device__ __forceinline__ unsigned xb_xcc_id() { return (unsigned)__builtin_amdgcn_s_getreg((3 << 11) | 20) & 0xFu; }
; __device__ __forceinline__ void transpose_item(const float* W, int K, int N, bf16* WT, int rs, int off, const float* sc, LAS float* scr, int item, int nblk, int lane, int swp) {
;     ...
;         const int ng = n0 + nn, t256 = ng >> 8, ts256 = (t256 == 2) ? 7 : (t256 == 7) ? 2 : t256, dr = swp ? ts256 * 256 + (ng & 255) : (ng / 128) * rs + off + (ng % 128);
;         *(v4u*)(WT + (size_t)dr * K + k0 + 8 * c) = o; }
; __device__ __forceinline__ void xcd_barrier(unsigned* bar, volatile __attribute__((address_space(3))) unsigned* st, int wave, int lane) {
;     asm volatile("s_waitcnt vmcnt(0)" ::: "memory");
;     __syncthreads();
;     if (wave == 0) {
;         __builtin_amdgcn_s_waitcnt(0);
;         const unsigned x = xb_xcc_id();
;         unsigned nloc = (unsigned)__builtin_amdgcn_readfirstlane((int)st[0]), nx = (unsigned)__builtin_amdgcn_readfirstlane((int)st[1]);
;         if (nloc == 0u) {
;             const unsigned G = gridDim.x; unsigned sp = 0u;
;             (void)xb_add_u(&bar[XB_XCNT(x)], 1u, lane);
.Lpj_b47:
	s_andn2_b64 vcc, exec, s[20:21]
	s_cbranch_vccnz .Lpj_b10
	s_ashr_i32 s2, s19, 3
	s_and_b32 s8, s39, 0xffffff00
	s_cmp_lg_u32 s2, 7
	s_cselect_b32 s8, s8, 0x200
	s_cmp_lg_u32 s2, 2
	s_cselect_b32 s2, s8, 0x700
	v_or_b32_sdwa v29, s2, v30 dst_sel:DWORD dst_unused:UNUSED_PAD src0_sel:DWORD src1_sel:BYTE_0
	s_branch .Lpj_b10
.Lpj_exit:
	v_readlane_b32 s4, v255, 20
	v_readlane_b32 s6, v255, 22
	v_readlane_b32 s7, v255, 23
	s_mov_b32 s68, s69
	s_mov_b64 s[12:13], s[6:7]
	v_mov_b32_e32 v0, v203
	s_waitcnt vmcnt(0)
	v_readlane_b32 s5, v255, 21
	v_readfirstlane_b32 s0, v0
	s_cmp_gt_u32 s0, 63
	s_waitcnt vmcnt(0) lgkmcnt(0)
	s_barrier
	s_cbranch_scc1 .LBB0_255
	s_add_u32 s10, s12, 0xe200000
	s_addc_u32 s11, s13, 0
	s_add_i32 s1, s68, 0x22000
	v_and_b32_e32 v1, 63, v0
	v_mov_b32_e32 v0, s1
	s_waitcnt vmcnt(0) expcnt(0) lgkmcnt(0)
	s_getreg_b32 s0, hwreg(HW_REG_XCC_ID, 0, 4)
	ds_read_b32 v0, v0
	s_add_i32 s68, s68, 0x22004
	s_and_b32 s0, s0, 15
	s_waitcnt lgkmcnt(0)
	v_readfirstlane_b32 s2, v0
	v_mov_b32_e32 v0, s68
	ds_read_b32 v0, v0
	s_cmp_lg_u32 s2, 0
	v_mov_b32_e32 v2, s2
	s_waitcnt lgkmcnt(0)
	v_readfirstlane_b32 s4, v0
	s_nop 1
	v_mov_b32_e32 v0, s4
	v_cmp_eq_u32_e64 s[4:5], 0, v1
	s_cbranch_scc1 .LBB0_205
	v_cmp_ne_u32_e32 vcc, 0, v1
	s_and_saveexec_b64 s[6:7], s[4:5]
	s_cbranch_execz .LBB0_191
	s_lshl_b32 s2, s0, 8
	s_add_u32 s8, s10, s2
	s_addc_u32 s9, s11, 0
	v_mov_b64_e32 v[2:3], s[8:9]
	flat_atomic_add v[2:3], v244 offset:1024
